# even in-proj epilogue: lane transpose through per-wave LDS slot so each store writes 64-B row segments
# speedup vs baseline: 1.0638x; 1.0053x over previous
; __device__ __forceinline__ u32x4 pack8(f32x4 a, f32x4 b) { u32x4 w; w.x = cvt_pk_bf16(a[0], a[1]); w.y = cvt_pk_bf16(a[2], a[3]); w.z = cvt_pk_bf16(b[0], b[1]); w.w = cvt_pk_bf16(b[2], b[3]); return w; }
;     __device__ __forceinline__ void operator()(const f32x4 (&acc)[2][2][4][2], const Unit& u, int wr, int wc, int fr_, int fq_, int slot) const {
;     ...
; #pragma unroll
;         for (int ai = 0; ai < 2; ++ai)
; #pragma unroll
;             for (int m = 0; m < 4; ++m) {
;                 bf16_t* rowp = P + (size_t)(u.pm * BM + ai * HALF + wr * 64 + m * 16 + fr) * EVEN_IN + col0;
; #pragma unroll
;                 for (int bj = 0; bj < 2; ++bj) {
;                     f32x4 v0 = acc[ai][bj][m][0] * rs[ai][m], v1 = acc[ai][bj][m][1] * rs[ai][m];
;                     *(u32x4*)(rowp + bj * HALF) = pack8(v0, v1);
;                 }
;                 asm volatile("" ::: "memory");
;             }
;     }
.LBB0_361:
	s_lshl_b32 s8, s91, 10
	s_and_b32 s8, s8, 0x400
	v_mov_b32_e32 v152, v160
	v_mov_b32_e32 v153, v159
	v_lshrrev_b32_e32 v200, 2, v159
	v_lshl_add_u32 v200, v160, 2, v200
	v_and_b32_e32 v201, 3, v159
	v_lshrrev_b32_e32 v202, 6, v233
	v_lshlrev_b32_e32 v202, 11, v202
	v_add_u32_e32 v202, 0x20000, v202
	v_mul_u32_u24_e32 v203, 0x50, v159
	v_lshl_add_u32 v203, v160, 4, v203
	v_add_u32_e32 v203, v203, v202
	v_mul_u32_u24_e32 v204, 0x50, v200
	v_lshl_add_u32 v204, v201, 4, v204
	v_add_u32_e32 v204, v204, v202
	s_add_i32 s8, s46, s8
	s_movk_i32 s13, 0x1200
	v_lshl_add_u32 v150, v153, 2, s8
	s_lshl_b32 s8, s22, 8
	s_or_b32 s8, s8, s35
	v_lshl_add_u32 v154, v201, 3, s8
	s_lshl_b32 s8, s90, 8
	s_add_i32 s8, s8, s33
	ds_read2_b32 v[164:165], v150 offset1:16
	ds_read2_b32 v[166:167], v150 offset0:32 offset1:48
	ds_read2_b32 v[156:157], v150 offset0:128 offset1:144
	ds_read2_b32 v[150:151], v150 offset0:160 offset1:176
	v_add_u32_e32 v172, s8, v200
	v_ashrrev_i32_e32 v155, 31, v154
	v_mov_b64_e32 v[152:153], s[0:1]
	v_mad_i64_i32 v[168:169], s[8:9], v172, s13, v[152:153]
	v_lshlrev_b64 v[154:155], 1, v[154:155]
	v_lshl_add_u64 v[168:169], v[168:169], 0, v[154:155]
	s_waitcnt lgkmcnt(0)
	v_pk_mul_f32 v[136:137], v[136:137], v[164:165] op_sel_hi:[1,0]
	v_pk_mul_f32 v[134:135], v[134:135], v[164:165] op_sel_hi:[1,0]
	v_pk_mul_f32 v[170:171], v[132:133], v[164:165] op_sel_hi:[1,0]
	v_pk_mul_f32 v[132:133], v[130:131], v[164:165] op_sel_hi:[1,0]
	v_cvt_pk_bf16_f32 v130, v134, v135
	v_cvt_pk_bf16_f32 v131, v136, v137
	v_pk_mul_f32 v[126:127], v[126:127], v[164:165] op_sel_hi:[1,0]
	v_cvt_pk_bf16_f32 v132, v132, v133
	v_cvt_pk_bf16_f32 v133, v170, v171
	ds_write_b128 v203, v[130:133]
	ds_read_b128 v[130:133], v204
	s_waitcnt lgkmcnt(0)
	global_store_dwordx4 v[168:169], v[130:133], off
	v_pk_mul_f32 v[128:129], v[128:129], v[164:165] op_sel_hi:[1,0]
	v_pk_mul_f32 v[104:105], v[104:105], v[166:167] op_sel_hi:[1,0]
	v_pk_mul_f32 v[130:131], v[120:121], v[164:165] op_sel_hi:[1,0]
	v_pk_mul_f32 v[120:121], v[118:119], v[164:165] op_sel_hi:[1,0]
	v_cvt_pk_bf16_f32 v118, v126, v127
	v_cvt_pk_bf16_f32 v119, v128, v129
	v_pk_mul_f32 v[92:93], v[92:93], v[166:167] op_sel_hi:[1,0]
	v_cvt_pk_bf16_f32 v120, v120, v121
	v_cvt_pk_bf16_f32 v121, v130, v131
	ds_write_b128 v203, v[118:121]
	ds_read_b128 v[118:121], v204
	s_waitcnt lgkmcnt(0)
	global_store_dwordx4 v[168:169], v[118:121], off offset:256
	v_pk_mul_f32 v[94:95], v[94:95], v[166:167] op_sel_hi:[1,0]
	v_pk_mul_f32 v[70:71], v[70:71], v[156:157] op_sel_hi:[1,0]
	v_add_u32_e32 v118, 16, v172
	v_mad_i64_i32 v[118:119], s[8:9], v118, s13, v[152:153]
	v_mov_b32_e32 v120, v165
	v_lshl_add_u64 v[118:119], v[118:119], 0, v[154:155]
	v_pk_mul_f32 v[124:125], v[124:125], v[120:121] op_sel_hi:[1,0]
	v_pk_mul_f32 v[122:123], v[122:123], v[120:121] op_sel_hi:[1,0]
	v_pk_mul_f32 v[126:127], v[116:117], v[120:121] op_sel_hi:[1,0]
	v_pk_mul_f32 v[116:117], v[114:115], v[120:121] op_sel_hi:[1,0]
	v_cvt_pk_bf16_f32 v114, v122, v123
	v_cvt_pk_bf16_f32 v115, v124, v125
	v_pk_mul_f32 v[108:109], v[108:109], v[120:121] op_sel_hi:[1,0]
	v_cvt_pk_bf16_f32 v116, v116, v117
	v_cvt_pk_bf16_f32 v117, v126, v127
	ds_write_b128 v203, v[114:117]
	ds_read_b128 v[114:117], v204
	s_waitcnt lgkmcnt(0)
	global_store_dwordx4 v[118:119], v[114:117], off
	v_pk_mul_f32 v[110:111], v[110:111], v[120:121] op_sel_hi:[1,0]
	v_pk_mul_f32 v[68:69], v[68:69], v[156:157] op_sel_hi:[1,0]
	v_pk_mul_f32 v[114:115], v[102:103], v[120:121] op_sel_hi:[1,0]
	v_pk_mul_f32 v[102:103], v[100:101], v[120:121] op_sel_hi:[1,0]
	v_cvt_pk_bf16_f32 v100, v108, v109
	v_cvt_pk_bf16_f32 v101, v110, v111
	v_pk_mul_f32 v[60:61], v[60:61], v[156:157] op_sel_hi:[1,0]
	v_cvt_pk_bf16_f32 v102, v102, v103
	v_cvt_pk_bf16_f32 v103, v114, v115
	ds_write_b128 v203, v[100:103]
	ds_read_b128 v[100:103], v204
	s_waitcnt lgkmcnt(0)
	global_store_dwordx4 v[118:119], v[100:103], off offset:256
	v_pk_mul_f32 v[62:63], v[62:63], v[156:157] op_sel_hi:[1,0]
	v_pk_mul_f32 v[40:41], v[40:41], v[150:151] op_sel_hi:[1,0]
	v_add_u32_e32 v100, 32, v172
	v_mad_i64_i32 v[100:101], s[8:9], v100, s13, v[152:153]
	v_lshl_add_u64 v[100:101], v[100:101], 0, v[154:155]
	v_pk_mul_f32 v[102:103], v[106:107], v[166:167] op_sel_hi:[1,0]
	v_pk_mul_f32 v[106:107], v[98:99], v[166:167] op_sel_hi:[1,0]
	v_pk_mul_f32 v[98:99], v[96:97], v[166:167] op_sel_hi:[1,0]
	v_cvt_pk_bf16_f32 v96, v104, v105
	v_cvt_pk_bf16_f32 v97, v102, v103
	v_pk_mul_f32 v[28:29], v[28:29], v[150:151] op_sel_hi:[1,0]
	v_cvt_pk_bf16_f32 v98, v98, v99
	v_cvt_pk_bf16_f32 v99, v106, v107
	ds_write_b128 v203, v[96:99]
	ds_read_b128 v[96:99], v204
	s_waitcnt lgkmcnt(0)
	global_store_dwordx4 v[100:101], v[96:99], off
	v_pk_mul_f32 v[30:31], v[30:31], v[150:151] op_sel_hi:[1,0]
	s_and_b64 vcc, exec, s[42:43]
	v_pk_mul_f32 v[96:97], v[86:87], v[166:167] op_sel_hi:[1,0]
	v_pk_mul_f32 v[86:87], v[84:85], v[166:167] op_sel_hi:[1,0]
	v_cvt_pk_bf16_f32 v84, v92, v93
	v_cvt_pk_bf16_f32 v85, v94, v95
	s_mov_b64 s[40:41], -1
	v_cvt_pk_bf16_f32 v86, v86, v87
	v_cvt_pk_bf16_f32 v87, v96, v97
	ds_write_b128 v203, v[84:87]
	ds_read_b128 v[84:87], v204
	s_waitcnt lgkmcnt(0)
	global_store_dwordx4 v[100:101], v[84:87], off offset:256
	s_nop 1
	v_add_u32_e32 v84, 48, v172
	v_mad_i64_i32 v[84:85], s[8:9], v84, s13, v[152:153]
	v_mov_b32_e32 v86, v167
	v_lshl_add_u64 v[84:85], v[84:85], 0, v[154:155]
	v_pk_mul_f32 v[90:91], v[90:91], v[86:87] op_sel_hi:[1,0]
	v_pk_mul_f32 v[88:89], v[88:89], v[86:87] op_sel_hi:[1,0]
	v_pk_mul_f32 v[92:93], v[82:83], v[86:87] op_sel_hi:[1,0]
	v_pk_mul_f32 v[82:83], v[80:81], v[86:87] op_sel_hi:[1,0]
	v_cvt_pk_bf16_f32 v80, v88, v89
	v_cvt_pk_bf16_f32 v81, v90, v91
	v_pk_mul_f32 v[76:77], v[76:77], v[86:87] op_sel_hi:[1,0]
	v_cvt_pk_bf16_f32 v82, v82, v83
	v_cvt_pk_bf16_f32 v83, v92, v93
	ds_write_b128 v203, v[80:83]
	ds_read_b128 v[80:83], v204
	s_waitcnt lgkmcnt(0)
; __device__ __forceinline__ u32x4 pack8(f32x4 a, f32x4 b) { u32x4 w; w.x = cvt_pk_bf16(a[0], a[1]); w.y = cvt_pk_bf16(a[2], a[3]); w.z = cvt_pk_bf16(b[0], b[1]); w.w = cvt_pk_bf16(b[2], b[3]); return w; }
;     __device__ __forceinline__ void post(int slot, int tid, const f32x4 (&r)[2]) const {
;         const f32x4 t = r[0] + r[1]; float s = (t[0] + t[1]) + (t[2] + t[3]);
;         s += __shfl_xor(s, 1);
;         if ((tid & 1) == 0) rst[slot * 256 + (tid >> 1)] = __builtin_amdgcn_rsqf(s * (1.0f / 1024.0f) + EPS);
;     __device__ __forceinline__ void operator()(const f32x4 (&acc)[2][2][4][2], const Unit& u, int wr, int wc, int fr_, int fq_, int slot) const {
;     ...
;         for (int ai = 0; ai < 2; ++ai)
; #pragma unroll
;             for (int m = 0; m < 4; ++m) {
;                 bf16_t* rowp = P + (size_t)(u.pm * BM + ai * HALF + wr * 64 + m * 16 + fr) * EVEN_IN + col0;
; #pragma unroll
;                 for (int bj = 0; bj < 2; ++bj) {
;                     f32x4 v0 = acc[ai][bj][m][0] * rs[ai][m], v1 = acc[ai][bj][m][1] * rs[ai][m];
;                     *(u32x4*)(rowp + bj * HALF) = pack8(v0, v1);
;                 }
;                 asm volatile("" ::: "memory");
;             }
;     }
	global_store_dwordx4 v[84:85], v[80:83], off
	v_pk_mul_f32 v[78:79], v[78:79], v[86:87] op_sel_hi:[1,0]
	s_nop 0
	v_pk_mul_f32 v[80:81], v[74:75], v[86:87] op_sel_hi:[1,0]
	v_pk_mul_f32 v[74:75], v[72:73], v[86:87] op_sel_hi:[1,0]
	v_cvt_pk_bf16_f32 v72, v76, v77
	v_cvt_pk_bf16_f32 v73, v78, v79
	s_nop 0
	v_cvt_pk_bf16_f32 v74, v74, v75
	v_cvt_pk_bf16_f32 v75, v80, v81
	ds_write_b128 v203, v[72:75]
	ds_read_b128 v[72:75], v204
	s_waitcnt lgkmcnt(0)
	global_store_dwordx4 v[84:85], v[72:75], off offset:256
	s_nop 1
	v_add_u32_e32 v72, 0x80, v172
	v_mad_i64_i32 v[72:73], s[8:9], v72, s13, v[152:153]
	v_lshl_add_u64 v[72:73], v[72:73], 0, v[154:155]
	v_pk_mul_f32 v[74:75], v[66:67], v[156:157] op_sel_hi:[1,0]
	v_pk_mul_f32 v[66:67], v[64:65], v[156:157] op_sel_hi:[1,0]
	v_cvt_pk_bf16_f32 v64, v68, v69
	v_cvt_pk_bf16_f32 v65, v70, v71
	s_nop 0
	v_cvt_pk_bf16_f32 v66, v66, v67
	v_cvt_pk_bf16_f32 v67, v74, v75
	ds_write_b128 v203, v[64:67]
	ds_read_b128 v[64:67], v204
	s_waitcnt lgkmcnt(0)
	global_store_dwordx4 v[72:73], v[64:67], off
	s_nop 1
	v_pk_mul_f32 v[64:65], v[54:55], v[156:157] op_sel_hi:[1,0]
	v_pk_mul_f32 v[54:55], v[52:53], v[156:157] op_sel_hi:[1,0]
	v_cvt_pk_bf16_f32 v52, v60, v61
	v_cvt_pk_bf16_f32 v53, v62, v63
	s_nop 0
	v_cvt_pk_bf16_f32 v54, v54, v55
	v_cvt_pk_bf16_f32 v55, v64, v65
	ds_write_b128 v203, v[52:55]
	ds_read_b128 v[52:55], v204
	s_waitcnt lgkmcnt(0)
	global_store_dwordx4 v[72:73], v[52:55], off offset:256
	s_nop 1
	v_add_u32_e32 v52, 0x90, v172
	v_mad_i64_i32 v[52:53], s[8:9], v52, s13, v[152:153]
	v_mov_b32_e32 v54, v157
	v_lshl_add_u64 v[52:53], v[52:53], 0, v[154:155]
	v_pk_mul_f32 v[58:59], v[58:59], v[54:55] op_sel_hi:[1,0]
	v_pk_mul_f32 v[56:57], v[56:57], v[54:55] op_sel_hi:[1,0]
	v_pk_mul_f32 v[60:61], v[50:51], v[54:55] op_sel_hi:[1,0]
	v_pk_mul_f32 v[50:51], v[48:49], v[54:55] op_sel_hi:[1,0]
	v_cvt_pk_bf16_f32 v48, v56, v57
	v_cvt_pk_bf16_f32 v49, v58, v59
	v_pk_mul_f32 v[44:45], v[44:45], v[54:55] op_sel_hi:[1,0]
	v_cvt_pk_bf16_f32 v50, v50, v51
	v_cvt_pk_bf16_f32 v51, v60, v61
	ds_write_b128 v203, v[48:51]
	ds_read_b128 v[48:51], v204
	s_waitcnt lgkmcnt(0)
	global_store_dwordx4 v[52:53], v[48:51], off
	v_pk_mul_f32 v[46:47], v[46:47], v[54:55] op_sel_hi:[1,0]
	s_nop 0
	v_pk_mul_f32 v[48:49], v[38:39], v[54:55] op_sel_hi:[1,0]
	v_pk_mul_f32 v[38:39], v[36:37], v[54:55] op_sel_hi:[1,0]
	v_cvt_pk_bf16_f32 v36, v44, v45
	v_cvt_pk_bf16_f32 v37, v46, v47
	s_nop 0
	v_cvt_pk_bf16_f32 v38, v38, v39
	v_cvt_pk_bf16_f32 v39, v48, v49
	ds_write_b128 v203, v[36:39]
	ds_read_b128 v[36:39], v204
	s_waitcnt lgkmcnt(0)
	global_store_dwordx4 v[52:53], v[36:39], off offset:256
	s_nop 1
	v_add_u32_e32 v36, 0xa0, v172
	v_mad_i64_i32 v[36:37], s[8:9], v36, s13, v[152:153]
	v_lshl_add_u64 v[36:37], v[36:37], 0, v[154:155]
	v_pk_mul_f32 v[38:39], v[42:43], v[150:151] op_sel_hi:[1,0]
	v_pk_mul_f32 v[42:43], v[34:35], v[150:151] op_sel_hi:[1,0]
	v_pk_mul_f32 v[34:35], v[32:33], v[150:151] op_sel_hi:[1,0]
	v_cvt_pk_bf16_f32 v32, v40, v41
	v_cvt_pk_bf16_f32 v33, v38, v39
	s_nop 0
	v_cvt_pk_bf16_f32 v34, v34, v35
	v_cvt_pk_bf16_f32 v35, v42, v43
	ds_write_b128 v203, v[32:35]
	ds_read_b128 v[32:35], v204
	s_waitcnt lgkmcnt(0)
	global_store_dwordx4 v[36:37], v[32:35], off
	s_nop 1
	v_pk_mul_f32 v[32:33], v[22:23], v[150:151] op_sel_hi:[1,0]
	v_pk_mul_f32 v[22:23], v[20:21], v[150:151] op_sel_hi:[1,0]
	v_cvt_pk_bf16_f32 v20, v28, v29
	v_cvt_pk_bf16_f32 v21, v30, v31
	s_nop 0
	v_cvt_pk_bf16_f32 v22, v22, v23
	v_cvt_pk_bf16_f32 v23, v32, v33
	ds_write_b128 v203, v[20:23]
	ds_read_b128 v[20:23], v204
	s_waitcnt lgkmcnt(0)
	global_store_dwordx4 v[36:37], v[20:23], off offset:256
	s_nop 1
	v_add_u32_e32 v20, 0xb0, v172
	v_mad_i64_i32 v[20:21], s[8:9], v20, s13, v[152:153]
	v_mov_b32_e32 v22, v151
	v_lshl_add_u64 v[20:21], v[20:21], 0, v[154:155]
	v_pk_mul_f32 v[26:27], v[26:27], v[22:23] op_sel_hi:[1,0]
	v_pk_mul_f32 v[24:25], v[24:25], v[22:23] op_sel_hi:[1,0]
	v_pk_mul_f32 v[28:29], v[18:19], v[22:23] op_sel_hi:[1,0]
	v_pk_mul_f32 v[18:19], v[16:17], v[22:23] op_sel_hi:[1,0]
	v_cvt_pk_bf16_f32 v16, v24, v25
	v_cvt_pk_bf16_f32 v17, v26, v27
	v_pk_mul_f32 v[14:15], v[14:15], v[22:23] op_sel_hi:[1,0]
	v_cvt_pk_bf16_f32 v18, v18, v19
	v_cvt_pk_bf16_f32 v19, v28, v29
	ds_write_b128 v203, v[16:19]
	ds_read_b128 v[16:19], v204
	s_waitcnt lgkmcnt(0)
	global_store_dwordx4 v[20:21], v[16:19], off
	v_pk_mul_f32 v[12:13], v[12:13], v[22:23] op_sel_hi:[1,0]
	v_readlane_b32 s13, v255, 49
	v_pk_mul_f32 v[16:17], v[10:11], v[22:23] op_sel_hi:[1,0]
	v_pk_mul_f32 v[10:11], v[8:9], v[22:23] op_sel_hi:[1,0]
	v_cvt_pk_bf16_f32 v8, v12, v13
	v_cvt_pk_bf16_f32 v9, v14, v15
	s_nop 0
	v_cvt_pk_bf16_f32 v10, v10, v11
	v_cvt_pk_bf16_f32 v11, v16, v17
	ds_write_b128 v203, v[8:11]
	ds_read_b128 v[8:11], v204
	s_waitcnt lgkmcnt(0)
	global_store_dwordx4 v[20:21], v[8:11], off offset:256
	s_cbranch_vccnz .LBB0_352
	s_waitcnt vmcnt(0)
	v_pk_add_f32 v[8:9], v[2:3], v[6:7]
	v_pk_add_f32 v[10:11], v[0:1], v[4:5]
	v_add_f32_e32 v8, v8, v9
	v_add_f32_e32 v10, v10, v11
	v_add_f32_e32 v8, v10, v8
	ds_bpermute_b32 v9, v158, v8
	s_and_saveexec_b64 s[40:41], s[38:39]
	s_cbranch_execz .LBB0_364
	s_waitcnt lgkmcnt(0)
	v_add_f32_e32 v8, v8, v9
	v_fmamk_f32 v8, v8, 0x3a800000, v217
	v_rsq_f32_e32 v8, v8
	s_lshl_b32 s8, s57, 10
	s_and_b32 s8, s8, 0x400
	v_add_u32_e32 v9, s8, v162
	ds_write_b32 v9, v8
